# half-unit GEMM instance peeled too (first MFMA per accumulator chain takes C=0, 63 zeroing moves gone)
# speedup vs baseline: 1.0066x; 1.0010x over previous
.LBB0_1290:
	s_add_u32 s8, s56, 0x100
	s_addc_u32 s45, s57, 0
	s_add_u32 s6, s52, 0x40080
	v_mov_b32_e32 v8, 0
	s_addc_u32 s7, s53, 0
	s_mov_b32 s55, -2
	s_waitcnt lgkmcnt(0)
	ds_read_b128 v[0:3], v96
	ds_read_b128 v[4:7], v96 offset:1024
	ds_read_b128 v[84:87], v96 offset:2048
	ds_read_b128 v[100:103], v96 offset:3072
	s_add_u32 s26, s6, 0xfffc0080
	s_addc_u32 s27, s7, -1
	s_cmp_eq_u32 s55, 12
	s_cselect_b32 s53, s47, s27
	s_cselect_b32 s52, s46, s26
	s_cselect_b32 s27, s49, s45
	s_cselect_b32 s26, s48, s8
	v_lshl_add_u64 v[88:89], s[6:7], 0, v[82:83]
	s_add_i32 m0, s28, 0xc000
	ds_read_b128 v[104:107], v97
	ds_read_b128 v[108:111], v97 offset:1024
	ds_read_b128 v[112:115], v97 offset:2048
	ds_read_b128 v[116:119], v97 offset:3072
	ds_read_b128 v[120:123], v97 offset:4096
	ds_read_b128 v[124:127], v97 offset:5120
	ds_read_b128 v[128:131], v97 offset:6144
	ds_read_b128 v[132:135], v97 offset:7168
	global_load_lds_dwordx4 v[88:89], off
	v_lshl_add_u64 v[88:89], s[6:7], 0, v[80:81]
	s_add_i32 m0, s28, 0xe000
	s_nop 0
	global_load_lds_dwordx4 v[88:89], off
	s_waitcnt vmcnt(6)
	s_waitcnt lgkmcnt(0)
	s_barrier
	s_setprio 1
	s_waitcnt lgkmcnt(0)
	v_mfma_f32_16x16x32_bf16 v[68:71], v[0:3], v[104:107], 0
	v_mfma_f32_16x16x32_bf16 v[64:67], v[84:87], v[104:107], 0
	v_mfma_f32_16x16x32_bf16 v[60:63], v[0:3], v[112:115], 0
	v_mfma_f32_16x16x32_bf16 v[56:59], v[84:87], v[112:115], 0
	v_mfma_f32_16x16x32_bf16 v[52:55], v[0:3], v[120:123], 0
	v_mfma_f32_16x16x32_bf16 v[48:51], v[84:87], v[120:123], 0
	v_mfma_f32_16x16x32_bf16 v[44:47], v[0:3], v[128:131], 0
	v_mfma_f32_16x16x32_bf16 v[40:43], v[84:87], v[128:131], 0
	v_mfma_f32_16x16x32_bf16 v[68:71], v[4:7], v[108:111], v[68:71]
	v_mfma_f32_16x16x32_bf16 v[64:67], v[100:103], v[108:111], v[64:67]
	v_mfma_f32_16x16x32_bf16 v[60:63], v[4:7], v[116:119], v[60:63]
	v_mfma_f32_16x16x32_bf16 v[56:59], v[100:103], v[116:119], v[56:59]
	v_mfma_f32_16x16x32_bf16 v[52:55], v[4:7], v[124:127], v[52:55]
	v_mfma_f32_16x16x32_bf16 v[48:51], v[100:103], v[124:127], v[48:51]
	v_mfma_f32_16x16x32_bf16 v[44:47], v[4:7], v[132:135], v[44:47]
	v_mfma_f32_16x16x32_bf16 v[40:43], v[100:103], v[132:135], v[40:43]
	s_setprio 0
	s_barrier
	s_add_i32 s56, s68, s39
	v_lshl_add_u64 v[88:89], s[26:27], 0, v[74:75]
	s_mov_b32 m0, s56
	ds_read_b128 v[104:107], v97 offset:16384
	ds_read_b128 v[108:111], v97 offset:17408
	ds_read_b128 v[112:115], v97 offset:18432
	ds_read_b128 v[116:119], v97 offset:19456
	ds_read_b128 v[120:123], v97 offset:20480
	ds_read_b128 v[124:127], v97 offset:21504
	ds_read_b128 v[128:131], v97 offset:22528
	ds_read_b128 v[132:135], v97 offset:23552
	global_load_lds_dwordx4 v[88:89], off
	v_lshl_add_u64 v[136:137], s[26:27], 0, v[78:79]
	s_add_i32 m0, s56, 0x2000
	v_lshl_add_u64 v[138:139], s[52:53], 0, v[72:73]
	global_load_lds_dwordx4 v[136:137], off
	s_mov_b32 m0, s28
	v_lshl_add_u64 v[140:141], s[52:53], 0, v[76:77]
	global_load_lds_dwordx4 v[138:139], off
	s_mov_b32 m0, s29
	s_nop 0
	global_load_lds_dwordx4 v[140:141], off
	s_waitcnt vmcnt(6)
	s_waitcnt lgkmcnt(0)
	s_barrier
	s_setprio 1
	s_waitcnt lgkmcnt(0)
	v_mfma_f32_16x16x32_bf16 v[36:39], v[0:3], v[104:107], 0
	v_mfma_f32_16x16x32_bf16 v[32:35], v[84:87], v[104:107], 0
	v_mfma_f32_16x16x32_bf16 v[28:31], v[0:3], v[112:115], 0
	v_mfma_f32_16x16x32_bf16 v[24:27], v[84:87], v[112:115], 0
	v_mfma_f32_16x16x32_bf16 v[20:23], v[0:3], v[120:123], 0
	v_mfma_f32_16x16x32_bf16 v[16:19], v[84:87], v[120:123], 0
	v_mfma_f32_16x16x32_bf16 v[0:3], v[0:3], v[128:131], 0
	v_mfma_f32_16x16x32_bf16 v[36:39], v[4:7], v[108:111], v[36:39]
	v_mfma_f32_16x16x32_bf16 v[32:35], v[100:103], v[108:111], v[32:35]
	v_mfma_f32_16x16x32_bf16 v[28:31], v[4:7], v[116:119], v[28:31]
	v_mfma_f32_16x16x32_bf16 v[24:27], v[100:103], v[116:119], v[24:27]
	v_mfma_f32_16x16x32_bf16 v[20:23], v[4:7], v[124:127], v[20:23]
	v_mfma_f32_16x16x32_bf16 v[16:19], v[100:103], v[124:127], v[16:19]
	v_mfma_f32_16x16x32_bf16 v[0:3], v[4:7], v[132:135], v[0:3]
	v_mfma_f32_16x16x32_bf16 v[4:7], v[84:87], v[128:131], 0
	v_mfma_f32_16x16x32_bf16 v[4:7], v[100:103], v[132:135], v[4:7]
	s_setprio 0
	s_barrier
	s_add_i32 s56, 0, 0x18000
	v_add_u32_e32 v90, s56, v91
	ds_read_b128 v[8:11], v90
	ds_read_b128 v[12:15], v90 offset:1024
	ds_read_b128 v[84:87], v90 offset:2048
	ds_read_b128 v[100:103], v90 offset:3072
	s_add_u32 s26, s52, 0x40000
	s_addc_u32 s27, s53, 0
	s_mov_b32 m0, s30
	v_lshl_add_u64 v[142:143], s[26:27], 0, v[72:73]
	ds_read_b128 v[104:107], v97 offset:32768
	ds_read_b128 v[108:111], v97 offset:33792
	ds_read_b128 v[112:115], v97 offset:34816
	ds_read_b128 v[116:119], v97 offset:35840
	ds_read_b128 v[120:123], v97 offset:36864
	ds_read_b128 v[124:127], v97 offset:37888
	ds_read_b128 v[128:131], v97 offset:38912
	ds_read_b128 v[132:135], v97 offset:39936
	global_load_lds_dwordx4 v[142:143], off
	v_lshl_add_u64 v[142:143], s[26:27], 0, v[76:77]
	s_mov_b32 m0, s31
	s_nop 0
	global_load_lds_dwordx4 v[142:143], off
	s_waitcnt vmcnt(6)
	s_waitcnt lgkmcnt(0)
	s_barrier
	s_setprio 1
	s_waitcnt lgkmcnt(0)
	v_mfma_f32_16x16x32_bf16 v[68:71], v[8:11], v[104:107], v[68:71]
	v_mfma_f32_16x16x32_bf16 v[64:67], v[84:87], v[104:107], v[64:67]
	v_mfma_f32_16x16x32_bf16 v[60:63], v[8:11], v[112:115], v[60:63]
	v_mfma_f32_16x16x32_bf16 v[56:59], v[84:87], v[112:115], v[56:59]
	v_mfma_f32_16x16x32_bf16 v[52:55], v[8:11], v[120:123], v[52:55]
	v_mfma_f32_16x16x32_bf16 v[48:51], v[84:87], v[120:123], v[48:51]
	v_mfma_f32_16x16x32_bf16 v[44:47], v[8:11], v[128:131], v[44:47]
	v_mfma_f32_16x16x32_bf16 v[40:43], v[84:87], v[128:131], v[40:43]
	v_mfma_f32_16x16x32_bf16 v[68:71], v[12:15], v[108:111], v[68:71]
	v_mfma_f32_16x16x32_bf16 v[64:67], v[100:103], v[108:111], v[64:67]
	v_mfma_f32_16x16x32_bf16 v[60:63], v[12:15], v[116:119], v[60:63]
	v_mfma_f32_16x16x32_bf16 v[56:59], v[100:103], v[116:119], v[56:59]
	v_mfma_f32_16x16x32_bf16 v[52:55], v[12:15], v[124:127], v[52:55]
	v_mfma_f32_16x16x32_bf16 v[48:51], v[100:103], v[124:127], v[48:51]
	v_mfma_f32_16x16x32_bf16 v[44:47], v[12:15], v[132:135], v[44:47]
	v_mfma_f32_16x16x32_bf16 v[40:43], v[100:103], v[132:135], v[40:43]
	s_setprio 0
	s_barrier
	s_add_i32 s26, s56, s39
	v_lshl_add_u64 v[88:89], v[88:89], 0, s[10:11]
	s_mov_b32 m0, s26
	ds_read_b128 v[104:107], v97 offset:49152
	ds_read_b128 v[108:111], v97 offset:50176
	ds_read_b128 v[112:115], v97 offset:51200
	ds_read_b128 v[116:119], v97 offset:52224
	ds_read_b128 v[120:123], v97 offset:53248
	ds_read_b128 v[124:127], v97 offset:54272
	ds_read_b128 v[128:131], v97 offset:55296
	ds_read_b128 v[132:135], v97 offset:56320
	global_load_lds_dwordx4 v[88:89], off
	v_lshl_add_u64 v[88:89], v[136:137], 0, s[10:11]
	s_add_i32 m0, s26, 0x2000
	s_nop 0
	global_load_lds_dwordx4 v[88:89], off
	v_lshl_add_u64 v[88:89], v[138:139], 0, s[10:11]
	s_mov_b32 m0, s62
	s_nop 0
	global_load_lds_dwordx4 v[88:89], off
	v_lshl_add_u64 v[88:89], v[140:141], 0, s[10:11]
	s_mov_b32 m0, s63
	s_nop 0
	global_load_lds_dwordx4 v[88:89], off
	s_waitcnt vmcnt(6)
	s_waitcnt lgkmcnt(0)
	s_barrier
	s_setprio 1
	s_waitcnt lgkmcnt(0)
	v_mfma_f32_16x16x32_bf16 v[36:39], v[8:11], v[104:107], v[36:39]
	v_mfma_f32_16x16x32_bf16 v[28:31], v[8:11], v[112:115], v[28:31]
	v_mfma_f32_16x16x32_bf16 v[20:23], v[8:11], v[120:123], v[20:23]
	v_mfma_f32_16x16x32_bf16 v[0:3], v[8:11], v[128:131], v[0:3]
	v_mfma_f32_16x16x32_bf16 v[36:39], v[12:15], v[108:111], v[36:39]
	v_mfma_f32_16x16x32_bf16 v[32:35], v[84:87], v[104:107], v[32:35]
	v_mfma_f32_16x16x32_bf16 v[28:31], v[12:15], v[116:119], v[28:31]
	v_mfma_f32_16x16x32_bf16 v[24:27], v[84:87], v[112:115], v[24:27]
	v_mfma_f32_16x16x32_bf16 v[20:23], v[12:15], v[124:127], v[20:23]
	v_mfma_f32_16x16x32_bf16 v[16:19], v[84:87], v[120:123], v[16:19]
	v_mfma_f32_16x16x32_bf16 v[12:15], v[12:15], v[132:135], v[0:3]
	v_mfma_f32_16x16x32_bf16 v[0:3], v[84:87], v[128:131], v[4:7]
	v_mfma_f32_16x16x32_bf16 v[32:35], v[100:103], v[108:111], v[32:35]
	v_mfma_f32_16x16x32_bf16 v[24:27], v[100:103], v[116:119], v[24:27]
	v_mfma_f32_16x16x32_bf16 v[16:19], v[100:103], v[124:127], v[16:19]
	v_mfma_f32_16x16x32_bf16 v[8:11], v[100:103], v[132:135], v[0:3]
	s_setprio 0
	s_barrier
	s_add_i32 s55, s55, 2
	s_add_u32 s8, s8, 0x100
	s_addc_u32 s45, s45, 0
	s_add_u32 s6, s6, 0x100
	s_addc_u32 s7, s7, 0
